# 4096 weight items per recurrence phase moved to the streamer WGs (4 per wave; wider margin in the idle slot)
# baseline (speedup 1.0000x reference)
; #define LAS __attribute__((address_space(3)))
; __global__ void __launch_bounds__(NTHR, 2) mega(const Args a) {
;     extern __shared__ __attribute__((aligned(16))) unsigned char lds_raw[];
;     LAS unsigned char* lds = (LAS unsigned char*)lds_raw;
;     const int wg0 = blockIdx.x, nwg0 = gridDim.x, tid = threadIdx.x;
;     for (int u = tid; u < (LDS_BYTES - LDSCTL_OFF) / 4; u += NTHR) ((LAS unsigned*)(lds + LDSCTL_OFF))[u] = 0u;
;     __syncthreads();
;     if (tid == 0) { const unsigned long long* src = (const unsigned long long*)&a.p;
; #pragma unroll
;         for (int i = 0; i < 25; ++i) *(LAS unsigned long long*)(lds + LDS_P_OFF + 8 * i) = src[i]; }
;     __syncthreads();
_Z4mega4Args:
	v_mov_b32_e32 v250, 0
	s_mov_b32 s3, 0x1e300
	v_writelane_b32 v250, s3, 2
	s_mov_b32 s3, 0x1e2ff
	v_writelane_b32 v250, s3, 3
	s_add_u32 s4, s0, 0xd0
	s_addc_u32 s5, s1, 0
	s_movk_i32 s3, 0x200
	v_writelane_b32 v249, s4, 0
	v_cmp_gt_u32_e32 vcc, s3, v0
	s_nop 0
	v_writelane_b32 v249, s5, 1
	s_and_saveexec_b64 s[6:7], vcc
	v_lshl_add_u32 v1, v0, 2, 0
	v_add_u32_e32 v1, 0x23800, v1
	v_mov_b32_e32 v2, 0
	ds_write_b32 v1, v2
	s_or_b64 exec, exec, s[6:7]
	s_waitcnt lgkmcnt(0)
	s_barrier
	v_cmp_eq_u32_e64 s[4:5], 0, v0
	s_mov_b64 s[22:23], exec
	s_nop 0
	v_writelane_b32 v249, s4, 2
	s_nop 1
	v_writelane_b32 v249, s5, 3
	s_and_b64 s[4:5], s[22:23], s[4:5]
	s_mov_b64 exec, s[4:5]
	s_cbranch_execz .LBB0_4
	s_load_dwordx16 s[4:19], s[0:1], 0x0
	s_add_i32 s20, 0, 0x23900
	s_load_dwordx16 s[48:63], s[0:1], 0x40
	v_mov_b32_e32 v1, s20
	s_add_i32 s20, 0, 0x23970
	s_waitcnt lgkmcnt(0)
	v_mov_b32_e32 v2, s4
	v_mov_b32_e32 v3, s5
	v_mov_b32_e32 v4, s6
	v_mov_b32_e32 v5, s7
	s_add_i32 s4, 0, 0x23910
	ds_write_b128 v1, v[2:5]
	v_mov_b32_e32 v2, s8
	v_mov_b32_e32 v3, s9
	v_mov_b32_e32 v4, s10
	v_mov_b32_e32 v5, s11
	v_mov_b32_e32 v1, s4
	s_add_i32 s4, 0, 0x23920
	ds_write_b128 v1, v[2:5]
	v_mov_b32_e32 v2, s12
	v_mov_b32_e32 v3, s13
	v_mov_b32_e32 v4, s14
	v_mov_b32_e32 v5, s15
	v_mov_b32_e32 v1, s4
	s_add_i32 s4, 0, 0x23930
	ds_write_b128 v1, v[2:5]
	v_mov_b32_e32 v2, s16
	v_mov_b32_e32 v3, s17
	v_mov_b32_e32 v4, s18
	v_mov_b32_e32 v5, s19
	v_mov_b32_e32 v1, s4
	s_add_i32 s4, 0, 0x23940
	ds_write_b128 v1, v[2:5]
	v_mov_b32_e32 v2, s48
	v_mov_b32_e32 v3, s49
	v_mov_b32_e32 v4, s50
	v_mov_b32_e32 v5, s51
	v_mov_b32_e32 v1, s4
	s_add_i32 s4, 0, 0x23950
	ds_write_b128 v1, v[2:5]
	v_mov_b32_e32 v2, s52
	v_mov_b32_e32 v3, s53
	v_mov_b32_e32 v4, s54
	v_mov_b32_e32 v5, s55
	v_mov_b32_e32 v1, s4
	s_add_i32 s4, 0, 0x23960
	ds_write_b128 v1, v[2:5]
	v_mov_b32_e32 v1, s4
	s_load_dwordx16 s[4:19], s[0:1], 0x80
	v_mov_b32_e32 v2, s56
	v_mov_b32_e32 v3, s57
	v_mov_b32_e32 v4, s58
	v_mov_b32_e32 v5, s59
	ds_write_b128 v1, v[2:5]
	v_mov_b32_e32 v2, s60
	v_mov_b32_e32 v3, s61
	v_mov_b32_e32 v4, s62
	v_mov_b32_e32 v5, s63
	v_mov_b32_e32 v1, s20
	ds_write_b128 v1, v[2:5]
	s_waitcnt lgkmcnt(0)
	v_mov_b32_e32 v2, s4
	s_add_i32 s4, 0, 0x23980
	v_mov_b32_e32 v3, s5
	v_mov_b32_e32 v4, s6
	v_mov_b32_e32 v5, s7
	v_mov_b32_e32 v1, s4
	s_add_i32 s4, 0, 0x23990
	ds_write_b128 v1, v[2:5]
	v_mov_b32_e32 v2, s8
	v_mov_b32_e32 v3, s9
	v_mov_b32_e32 v4, s10
	v_mov_b32_e32 v5, s11
	v_mov_b32_e32 v1, s4
	s_add_i32 s4, 0, 0x239a0
	ds_write_b128 v1, v[2:5]
	v_mov_b32_e32 v1, s4
	s_load_dwordx2 s[4:5], s[0:1], 0xc0
	v_mov_b32_e32 v2, s12
	v_mov_b32_e32 v3, s13
	v_mov_b32_e32 v4, s14
	v_mov_b32_e32 v5, s15
	s_add_i32 s6, 0, 0x239b0
	ds_write_b128 v1, v[2:5]
	v_mov_b32_e32 v2, s16
	v_mov_b32_e32 v3, s17
	v_mov_b32_e32 v4, s18
	v_mov_b32_e32 v5, s19
	v_mov_b32_e32 v1, s6
	s_add_i32 s6, 0, 0x239c0
	ds_write_b128 v1, v[2:5]
	v_mov_b32_e32 v1, s6
	s_waitcnt lgkmcnt(0)
	v_mov_b64_e32 v[2:3], s[4:5]
	ds_write_b64 v1, v[2:3]

; #define LAS __attribute__((address_space(3)))
; __device__ __forceinline__ void phase_prologue(const P& p, unsigned char* ws, LAS unsigned char* lds, int wg, int nwg) {
;     ...
;     for (int it = gw; it < DEPTH * I_LAYER; it += NGW) {
;         const int l = it / I_LAYER; int r = it % I_LAYER;
; __device__ __forceinline__ void phase_rec(const P& p, unsigned char* ws, int l, LAS unsigned char* lds, int wg, int nwg) {
;     int lrank = wg, nloop = nwg, srank = wg, nstr = nwg;
;     const bool split = nwg >= 16;
;     if (split) { const int grp = wg >> 3, ngrp = (nwg + 7) >> 3, nlg = (ngrp + 1) >> 1;
;         const int full_l = nlg * 8 - ((ngrp & 1) ? (ngrp * 8 - nwg) : 0), full_s = nwg - full_l;
;         nloop = full_l; nstr = full_s; lrank = (grp >> 1) * 8 + (wg & 7); srank = (grp >> 1) * 8 + (wg & 7);
;         if (grp & 1) lrank = 1 << 30; else srank = 1 << 30; }
;     for (int rl = 0; rl < REP_LOOP; ++rl) for (int tk = lrank; tk < 128; tk += nloop) rec_loop_task(p, ws, l, lds, tk);
.LBB0_1145:
	v_readlane_b32 s0, v248, 27
	s_cmp_gt_u32 s0, 2
	s_cbranch_scc1 .Lcv_skip
	v_readlane_b32 s1, v248, 19
	s_bitcmp1_b32 s1, 3
	s_cbranch_scc0 .Lcv_skip
	s_waitcnt lgkmcnt(0)
	s_barrier
	v_writelane_b32 v251, s3, 0
	v_writelane_b32 v251, s4, 1
	v_writelane_b32 v251, s5, 2
	v_writelane_b32 v251, s6, 3
	v_writelane_b32 v251, s7, 4
	v_writelane_b32 v251, s8, 5
	v_writelane_b32 v251, s9, 6
	v_writelane_b32 v251, s10, 7
	v_writelane_b32 v251, s11, 8
	v_writelane_b32 v251, s12, 9
	v_writelane_b32 v251, s13, 10
	v_writelane_b32 v251, s14, 11
	v_writelane_b32 v251, s15, 12
	v_writelane_b32 v251, s16, 13
	v_writelane_b32 v251, s17, 14
	v_writelane_b32 v251, s18, 15
	v_writelane_b32 v251, s19, 16
	v_writelane_b32 v251, s20, 17
	v_writelane_b32 v251, s21, 18
	v_writelane_b32 v251, s23, 20
	v_writelane_b32 v251, s24, 21
	v_writelane_b32 v251, s25, 22
	v_writelane_b32 v251, s26, 23
	v_writelane_b32 v251, s27, 24
	v_writelane_b32 v251, s28, 25
	v_writelane_b32 v251, s29, 26
	v_writelane_b32 v251, s30, 27
	v_writelane_b32 v251, s31, 28
	v_writelane_b32 v251, s32, 29
	v_writelane_b32 v251, s33, 30
	v_writelane_b32 v251, s34, 31
	v_writelane_b32 v251, s35, 32
	v_writelane_b32 v251, s36, 33
	v_writelane_b32 v251, s37, 34
	v_writelane_b32 v251, s38, 35
	v_writelane_b32 v251, s39, 36
	v_writelane_b32 v251, s40, 37
	v_writelane_b32 v251, s41, 38
	v_writelane_b32 v251, s42, 39
	v_writelane_b32 v251, s43, 40
	v_writelane_b32 v251, s44, 41
	v_writelane_b32 v251, s45, 42
	v_writelane_b32 v251, s46, 43
	v_writelane_b32 v251, s47, 44
	v_writelane_b32 v251, s48, 45
	v_writelane_b32 v251, s49, 46
	v_writelane_b32 v251, s50, 47
	v_writelane_b32 v251, s51, 48
	v_writelane_b32 v251, s52, 49
	v_writelane_b32 v251, s53, 50
	v_writelane_b32 v251, s54, 51
	v_writelane_b32 v251, s55, 52
	v_writelane_b32 v251, s56, 53
	v_writelane_b32 v251, s57, 54
	v_writelane_b32 v251, s58, 55
	v_writelane_b32 v251, s59, 56
	v_writelane_b32 v251, s60, 57
	v_writelane_b32 v251, s61, 58
	v_writelane_b32 v251, s62, 59
	v_writelane_b32 v251, s63, 60
	v_writelane_b32 v251, s64, 61
	v_writelane_b32 v251, s65, 62
	v_writelane_b32 v251, s66, 63
	v_writelane_b32 v252, s67, 0
	v_writelane_b32 v252, s68, 1
	v_writelane_b32 v252, s69, 2
	v_writelane_b32 v252, s70, 3
	v_writelane_b32 v252, s71, 4
	v_writelane_b32 v252, s72, 5
	v_writelane_b32 v252, s73, 6
	v_writelane_b32 v252, s74, 7
	v_writelane_b32 v252, s75, 8
	v_writelane_b32 v252, s76, 9
	v_writelane_b32 v252, s77, 10
	v_writelane_b32 v252, s78, 11
	v_writelane_b32 v252, s79, 12
	v_writelane_b32 v252, s80, 13
	v_writelane_b32 v252, s81, 14
	v_writelane_b32 v252, s82, 15
	v_writelane_b32 v252, s83, 16
	v_writelane_b32 v252, s84, 17
	v_writelane_b32 v252, s85, 18
	v_writelane_b32 v252, s86, 19
	v_writelane_b32 v252, s87, 20
	v_writelane_b32 v252, s88, 21
	v_writelane_b32 v252, s89, 22
	v_writelane_b32 v252, s90, 23
	v_writelane_b32 v252, s91, 24
	v_writelane_b32 v252, s92, 25
	v_writelane_b32 v252, s93, 26
	v_writelane_b32 v252, s94, 27
	v_writelane_b32 v252, s95, 28
	v_writelane_b32 v252, s96, 29
	v_writelane_b32 v252, s97, 30
	v_writelane_b32 v252, s98, 31
	v_writelane_b32 v252, s99, 32
	v_mov_b32_e32 v253, v1
	s_lshr_b32 s22, s1, 4
	s_lshl_b32 s22, s22, 3
	s_and_b32 s1, s1, 7
	s_or_b32 s1, s22, s1
	v_writelane_b32 v250, s1, 4
	s_mul_i32 s22, s0, 0x1000
	s_add_i32 s22, s22, 0x1e300
	v_writelane_b32 v250, s22, 1
	s_add_i32 s22, s22, 0x1000
	v_writelane_b32 v250, s22, 2
	s_add_i32 s22, s22, -1
	v_writelane_b32 v250, s22, 3
	s_mov_b32 s22, 1
	v_writelane_b32 v250, s22, 0
	s_branch .Lcv_entry
